# NA fixed-softmax loop: 15 packed f32 adds (row sums) converted into scalar pairs (identical results)
# baseline (speedup 1.0000x reference)
.LBB0_1263:
	v_add_f32_e32 v64, 0, v148
	v_add_f32_e32 v65, 0, v177
	v_add_f32_e32 v64, v64, v179
	v_add_f32_e32 v65, v65, v202
	v_add_f32_e32 v64, v64, v203
	v_add_f32_e32 v65, v65, v204
	v_add_f32_e32 v148, v64, v205
	v_add_f32_e32 v64, v65, v230
	v_mov_b32_e32 v65, v149
	v_add_f32_e32 v66, v148, v74
	v_add_f32_e32 v67, v149, v75
	v_add_f32_e32 v64, v64, v72
	v_add_f32_e32 v65, v65, v73
	v_add_f32_e32 v66, v66, v68
	v_add_f32_e32 v67, v67, v69
	v_add_f32_e32 v64, v64, v70
	v_add_f32_e32 v65, v65, v71
	v_add_f32_e32 v66, v66, v78
	v_add_f32_e32 v67, v67, v79
	v_add_f32_e32 v64, v64, v198
	v_add_f32_e32 v65, v65, v199
	v_add_f32_e32 v66, v66, v76
	v_add_f32_e32 v67, v67, v77
	v_add_f32_e32 v64, v64, v200
	v_add_f32_e32 v65, v65, v201
	v_readlane_b32 s14, v254, 41
	v_add_f32_e32 v64, v66, v64
	v_add_f32_e32 v65, v67, v65
	v_readlane_b32 s15, v254, 42
	v_add_f32_e32 v190, v190, v64
	v_add_f32_e32 v191, v191, v65
	v_mfma_f32_32x32x16_bf16 v[64:79], v[140:143], v[96:99], 0
	s_add_i32 s12, s12, 2
	v_add_u32_e32 v233, 0x80, v233
	v_add_u32_e32 v228, 0x7c, v228
	v_add_u32_e32 v229, 0x7c, v229
	s_andn2_b64 vcc, exec, s[8:9]
	s_waitcnt lgkmcnt(0)
	v_mfma_f32_32x32x16_bf16 v[64:79], v[136:139], v[100:103], v[64:79]
	v_mfma_f32_32x32x16_bf16 v[64:79], v[128:131], v[104:107], v[64:79]
	v_mfma_f32_32x32x16_bf16 v[64:79], v[132:135], v[108:111], v[64:79]
	s_nop 11
	ds_read2_b32 v[72:73], v175 offset0:32 offset1:33
	s_waitcnt lgkmcnt(0)
	v_add_f32_e32 v64, v64, v72
	v_cndmask_b32_e64 v71, v216, v64, s[60:61]
	v_add_f32_e32 v64, v65, v73
	v_cndmask_b32_e64 v72, v216, v64, s[62:63]
	ds_read2_b32 v[64:65], v175 offset0:34 offset1:35
	v_exp_f32_e32 v194, v71
	v_exp_f32_e32 v192, v72
	s_waitcnt lgkmcnt(0)
	v_add_f32_e32 v64, v66, v64
	v_cndmask_b32_e64 v66, v216, v64, s[64:65]
	v_add_f32_e32 v64, v67, v65
	v_cndmask_b32_e64 v67, v216, v64, s[66:67]
	ds_read2_b32 v[64:65], v175 offset0:36 offset1:37
	v_exp_f32_e32 v198, v66
	v_exp_f32_e32 v196, v67
	s_waitcnt lgkmcnt(0)
	v_add_f32_e32 v64, v68, v64
	ds_read_b32 v68, v175 offset:152
	v_add_f32_e32 v65, v69, v65
	v_cndmask_b32_e64 v64, v216, v64, s[68:69]
	v_cndmask_b32_e64 v65, v216, v65, s[70:71]
	v_exp_f32_e32 v202, v64
	s_waitcnt lgkmcnt(0)
	v_add_f32_e32 v68, v70, v68
	v_cndmask_b32_e64 v68, v216, v68, s[72:73]
	v_exp_f32_e32 v200, v65
	v_exp_f32_e32 v204, v68
	v_mfma_f32_32x32x16_bf16 v[64:79], v[140:143], v[112:115], 0
	v_mfma_f32_32x32x16_bf16 v[64:79], v[136:139], v[116:119], v[64:79]
	v_mfma_f32_32x32x16_bf16 v[64:79], v[128:131], v[120:123], v[64:79]
	ds_read2_b32 v[128:129], v159 offset0:32 offset1:33
	v_mfma_f32_32x32x16_bf16 v[64:79], v[132:135], v[124:127], v[64:79]
	s_waitcnt lgkmcnt(0)
	s_nop 10
	v_add_f32_e32 v64, v64, v128
	v_cndmask_b32_e64 v128, v216, v64, s[14:15]
	v_add_f32_e32 v64, v65, v129
	v_cndmask_b32_e64 v129, v216, v64, s[74:75]
	ds_read2_b32 v[64:65], v159 offset0:34 offset1:35
	v_add_u32_e32 v231, 0x10000, v231
	v_add_u32_e32 v232, 0x10000, v232
	s_waitcnt lgkmcnt(0)
	v_add_f32_e32 v64, v66, v64
	v_cndmask_b32_e64 v66, v216, v64, s[76:77]
	v_add_f32_e32 v64, v67, v65
	v_cndmask_b32_e64 v67, v216, v64, s[78:79]
	ds_read2_b32 v[64:65], v159 offset0:36 offset1:37
	v_exp_f32_e32 v130, v66
	v_exp_f32_e32 v131, v67
	s_waitcnt lgkmcnt(0)
	v_add_f32_e32 v64, v68, v64
	v_cndmask_b32_e64 v68, v216, v64, s[80:81]
	v_add_f32_e32 v64, v69, v65
	v_cndmask_b32_e64 v69, v216, v64, s[82:83]
	ds_read2_b32 v[64:65], v159 offset0:38 offset1:39
	s_waitcnt lgkmcnt(0)
	v_add_f32_e32 v64, v70, v64
	v_cndmask_b32_e64 v70, v216, v64, s[84:85]
	v_add_f32_e32 v64, v71, v65
	v_cndmask_b32_e64 v71, v216, v64, s[86:87]
	ds_read2_b32 v[64:65], v159 offset0:48 offset1:49
	v_exp_f32_e32 v132, v70
	v_exp_f32_e32 v133, v71
	v_mov_b32_e32 v70, v149
	s_waitcnt lgkmcnt(0)
	v_add_f32_e32 v64, v72, v64
	v_cndmask_b32_e64 v72, v216, v64, s[88:89]
	v_add_f32_e32 v64, v73, v65
	v_cndmask_b32_e64 v73, v216, v64, s[90:91]
	ds_read2_b32 v[64:65], v159 offset0:50 offset1:51
	v_exp_f32_e32 v72, v72
	v_exp_f32_e32 v195, v73
	s_waitcnt lgkmcnt(0)
	v_add_f32_e32 v64, v74, v64
	v_cndmask_b32_e64 v74, v216, v64, s[92:93]
	v_add_f32_e32 v64, v75, v65
	v_cndmask_b32_e64 v75, v216, v64, s[94:95]
	ds_read2_b32 v[64:65], v159 offset0:52 offset1:53
	v_exp_f32_e32 v193, v74
	v_exp_f32_e32 v199, v75
	s_waitcnt lgkmcnt(0)
	v_add_f32_e32 v64, v76, v64
	v_cndmask_b32_e64 v76, v216, v64, s[96:97]
	v_add_f32_e32 v64, v77, v65
	v_cndmask_b32_e64 v77, v216, v64, s[2:3]
	ds_read2_b32 v[64:65], v159 offset0:54 offset1:55
	v_exp_f32_e32 v197, v76
	v_exp_f32_e32 v203, v77
	s_waitcnt lgkmcnt(0)
	v_add_f32_e32 v64, v78, v64
	v_exp_f32_e32 v78, v128
	v_add_f32_e32 v65, v79, v65
	v_exp_f32_e32 v79, v129
	v_cndmask_b32_e64 v64, v216, v64, s[4:5]
	v_add_f32_e32 v128, 0, v78
	v_add_f32_e32 v66, v128, v130
	v_add_f32_e32 v129, 0, v79
	v_exp_f32_e32 v128, v68
	v_add_f32_e32 v67, v129, v131
	v_exp_f32_e32 v129, v69
	v_cndmask_b32_e64 v65, v216, v65, s[0:1]
	v_add_f32_e32 v66, v66, v128
	v_add_f32_e32 v66, v66, v132
	v_add_f32_e32 v67, v67, v129
	v_add_f32_e32 v69, v67, v133
	v_add_f32_e32 v71, v66, v72
	v_exp_f32_e32 v201, v64
	v_exp_f32_e32 v205, v65
	v_cvt_pk_bf16_f32 v64, v194, v192
	v_cvt_pk_bf16_f32 v65, v198, v196
	v_cvt_pk_bf16_f32 v66, v202, v200
	v_cvt_pk_bf16_f32 v67, v204, 0
	v_mov_b32_e32 v68, v149
	v_add_f32_e32 v68, v68, v194
	v_add_f32_e32 v69, v69, v195
	v_mfma_f32_32x32x16_bf16 v[32:47], v[92:95], v[64:67], v[32:47]
	v_add_f32_e64 v70, v70, v192
	v_add_f32_e64 v71, v71, v193
	v_add_f32_e64 v68, v68, v198
	v_add_f32_e64 v69, v69, v199
	v_add_f32_e64 v70, v70, v196
	v_add_f32_e64 v71, v71, v197
	v_add_f32_e32 v68, v68, v202
	v_add_f32_e32 v69, v69, v203
	v_add_f32_e32 v70, v70, v200
	v_add_f32_e32 v71, v71, v201
	v_add_f32_e32 v68, v68, v204
	v_add_f32_e32 v69, v69, v205
	v_mfma_f32_32x32x16_bf16 v[48:63], v[88:91], v[64:67], v[48:63]
	v_cvt_pk_bf16_f32 v64, v78, v79
	v_cvt_pk_bf16_f32 v65, v130, v131
	v_cvt_pk_bf16_f32 v66, v128, v129
	v_cvt_pk_bf16_f32 v67, v132, v133
	v_add_f32_e64 v68, v70, v68
	v_add_f32_e64 v69, v71, v69
	v_add_f32_e32 v190, v190, v68
	v_add_f32_e32 v191, v191, v69
	v_mfma_f32_32x32x16_bf16 v[0:15], v[92:95], v[64:67], v[0:15]
	v_mfma_f32_32x32x16_bf16 v[16:31], v[88:91], v[64:67], v[16:31]
	v_cvt_pk_bf16_f32 v64, v72, v195
	v_cvt_pk_bf16_f32 v65, v193, v199
	v_cvt_pk_bf16_f32 v66, v197, v203
	v_cvt_pk_bf16_f32 v67, v201, v205
	s_nop 1
	v_mfma_f32_32x32x16_bf16 v[0:15], v[84:87], v[64:67], v[0:15]
	v_mfma_f32_32x32x16_bf16 v[16:31], v[80:83], v[64:67], v[16:31]
	s_cbranch_vccz .LBB0_1253
